# dropped the grid-level wait after FFN down round 0 in both layers (the following up rounds are independent of it); LDS-DMA ring attention kept
# speedup vs baseline: 1.0180x; 1.0046x over previous
; __device__ __forceinline__ unsigned xb_ld(unsigned* p)              { return __hip_atomic_load(p, __ATOMIC_RELAXED, __HIP_MEMORY_SCOPE_AGENT); }
; __device__ __forceinline__ unsigned xb_add(unsigned* p, unsigned v) { return __hip_atomic_fetch_add(p, v, __ATOMIC_RELAXED, __HIP_MEMORY_SCOPE_AGENT); }
; #define XB_SPIN(cond, bar) do { unsigned _sp = 0; while (cond) { __builtin_amdgcn_s_sleep(1); \
;     if ((++_sp & 255u) == 0u) { if (xb_ld(&(bar)[XB_TMO])) break; if (_sp > XB_SPIN_CAP) { atomicAdd(&(bar)[XB_TMO], 1u); break; } } } } while (0)
; __device__ __forceinline__ void xcd_local_barrier(const XcdBarrier& b) {
;     asm volatile("s_waitcnt vmcnt(0)" ::: "memory");
;     __syncthreads();
;     if (threadIdx.x == 0) {
;         unsigned* bar = b.bar;
;         __builtin_amdgcn_s_waitcnt(0);
;         const unsigned nloc = b.st[0];
;         const unsigned old = xb_add(&bar[XL_SUB(b.x)], 1u);
;         const unsigned gen = old / nloc;
;         if (old + 1u == (gen + 1u) * nloc) xb_add(&bar[XL_GEN(b.x)], 1u);
;         else XB_SPIN(xb_ld(&bar[XL_GEN(b.x)]) == gen, bar);
;         __builtin_amdgcn_fence(__ATOMIC_ACQUIRE, "agent");
;         asm volatile("s_waitcnt vmcnt(0)" ::: "memory");
.LBB0_1023:
	s_waitcnt vmcnt(0)
	s_waitcnt vmcnt(0)
	s_barrier
	s_and_saveexec_b64 s[6:7], s[0:1]
	s_branch .LBB0_1041
	s_add_i32 s8, 0, 0x20400
	v_mov_b32_e32 v0, s8
	s_waitcnt vmcnt(0) expcnt(0) lgkmcnt(0)
	ds_read_b32 v0, v0
	s_mov_b64 s[18:19], exec
	s_lshl_b32 s8, s33, 8
	v_mbcnt_lo_u32_b32 v1, s18, 0
	s_add_u32 s8, s50, s8
	v_mbcnt_hi_u32_b32 v1, s19, v1
	s_addc_u32 s9, s51, 0
	v_cmp_eq_u32_e32 vcc, 0, v1
	s_and_saveexec_b64 s[20:21], vcc
	s_cbranch_execz .LBB0_1026
	s_bcnt1_i32_b64 s18, s[18:19]
	v_mov_b32_e32 v2, 0x3000
	v_mov_b32_e32 v3, s18
	global_atomic_add v2, v2, v3, s[8:9] offset:1536 sc0

; __device__ __forceinline__ unsigned xb_ld(unsigned* p)              { return __hip_atomic_load(p, __ATOMIC_RELAXED, __HIP_MEMORY_SCOPE_AGENT); }
; __device__ __forceinline__ unsigned xb_add(unsigned* p, unsigned v) { return __hip_atomic_fetch_add(p, v, __ATOMIC_RELAXED, __HIP_MEMORY_SCOPE_AGENT); }
; #define XB_SPIN(cond, bar) do { unsigned _sp = 0; while (cond) { __builtin_amdgcn_s_sleep(1); \
;     if ((++_sp & 255u) == 0u) { if (xb_ld(&(bar)[XB_TMO])) break; if (_sp > XB_SPIN_CAP) { atomicAdd(&(bar)[XB_TMO], 1u); break; } } } } while (0)
; __device__ __forceinline__ void xcd_local_barrier(const XcdBarrier& b) {
;     asm volatile("s_waitcnt vmcnt(0)" ::: "memory");
;     __syncthreads();
;     if (threadIdx.x == 0) {
;         unsigned* bar = b.bar;
;         __builtin_amdgcn_s_waitcnt(0);
;         const unsigned nloc = b.st[0];
;         const unsigned old = xb_add(&bar[XL_SUB(b.x)], 1u);
;         const unsigned gen = old / nloc;
;         if (old + 1u == (gen + 1u) * nloc) xb_add(&bar[XL_GEN(b.x)], 1u);
;         else XB_SPIN(xb_ld(&bar[XL_GEN(b.x)]) == gen, bar);
;         __builtin_amdgcn_fence(__ATOMIC_ACQUIRE, "agent");
;         asm volatile("s_waitcnt vmcnt(0)" ::: "memory");
.LBB0_1955:
	s_waitcnt vmcnt(0)
	s_waitcnt vmcnt(0)
	s_barrier
	s_and_saveexec_b64 s[6:7], s[0:1]
	s_branch .LBB0_1973
	s_add_i32 s8, 0, 0x20400
	v_mov_b32_e32 v0, s8
	s_waitcnt vmcnt(0) expcnt(0) lgkmcnt(0)
	ds_read_b32 v0, v0
	s_mov_b64 s[14:15], exec
	s_lshl_b32 s8, s33, 8
	v_mbcnt_lo_u32_b32 v1, s14, 0
	s_add_u32 s8, s50, s8
	v_mbcnt_hi_u32_b32 v1, s15, v1
	s_addc_u32 s9, s51, 0
	v_cmp_eq_u32_e32 vcc, 0, v1
	s_and_saveexec_b64 s[18:19], vcc
	s_cbranch_execz .LBB0_1958
	s_bcnt1_i32_b64 s14, s[14:15]
	v_mov_b32_e32 v2, 0x3000
	v_mov_b32_e32 v3, s14
	global_atomic_add v2, v2, v3, s[8:9] offset:1536 sc0
